# safe2 + pass-1 Q loads issued at the start of the pass-0 epilogue, before the 16 scratch stores (waits re-counted +16)
# baseline (speedup 1.0000x reference)
; #define GAS __attribute__((address_space(1)))
; template <bool GRPB> __device__ __forceinline__ void attn_pass(const float mbK, const float bmax2, const int pass, float* __restrict__ scr, bf16* __restrict__ mixrow, const float lam, const float* __restrict__ gsub, const float one_m_li, ...
;     ...
;   const bf16* Qw = Qb + (long)(wid * 32 + r32) * LDK + hi * 8;
; #pragma unroll
;   for (int d0 = 0; d0 < 4; ++d0) qr[d0] = *(const GAS bf16x8*)(Qw + d0 * 16);
;     ...
;   if (pass == 0) {
; #pragma unroll
;     for (int r4 = 0; r4 < 4; ++r4) { const f32x4 lv = *(const f32x4*)(li_e + 8 * r4 + 4 * hi);
;       const f32x4 rl = (f32x4){__builtin_amdgcn_rcpf(lv[0]), __builtin_amdgcn_rcpf(lv[1]), __builtin_amdgcn_rcpf(lv[2]), __builtin_amdgcn_rcpf(lv[3])};
; #pragma unroll
;       for (int d0 = 0; d0 < 4; ++d0) scr4[d0 * 4 + r4] = (f32x4){o[d0][4 * r4 + 0] * rl[0], o[d0][4 * r4 + 1] * rl[1], o[d0][4 * r4 + 2] * rl[2], o[d0][4 * r4 + 3] * rl[3]}; }
.LBB0_321:
	s_or_b64 exec, exec, s[0:1]
	s_movk_i32 s74, 0xffe0
	v_ashrrev_i32_e32 v96, 1, v232
	v_bfi_b32 v96, s74, v96, v232
	v_ashrrev_i32_e32 v97, 31, v96
	v_lshlrev_b64 v[96:97], 13, v[96:97]
	v_lshl_add_u64 v[96:97], s[52:53], 0, v[96:97]
	v_bfe_u32 v98, v232, 5, 1
	v_lshlrev_b32_e32 v98, 4, v98
	v_mov_b32_e32 v99, 0
	v_lshl_add_u64 v[96:97], v[96:97], 0, v[98:99]
	global_load_dwordx4 v[164:167], v[96:97], off offset:128
	global_load_dwordx4 v[160:163], v[96:97], off offset:160
	global_load_dwordx4 v[152:155], v[96:97], off offset:192
	global_load_dwordx4 v[156:159], v[96:97], off offset:224
	s_waitcnt lgkmcnt(0)
	v_add_u32_e32 v74, v66, v200
	ds_read_b128 v[66:69], v74
	ds_read_b128 v[70:73], v74 offset:32
	v_ashrrev_i32_e32 v147, 31, v146
	v_lshlrev_b64 v[0:1], 8, v[146:147]
	v_lshl_add_u64 v[0:1], s[40:41], 0, v[0:1]
	s_waitcnt lgkmcnt(1)
	v_rcp_f32_e32 v66, v66
	v_rcp_f32_e32 v67, v67
	v_rcp_f32_e32 v68, v68
	v_rcp_f32_e32 v69, v69
	v_readlane_b32 s0, v254, 39
	v_pk_mul_f32 v[2:3], v[2:3], v[66:67]
	v_mov_b32_e32 v146, v232
	v_pk_mul_f32 v[4:5], v[4:5], v[68:69]
	global_store_dwordx4 v[0:1], v[2:5], off
	v_mov_b32_e32 v201, v144
	s_nop 0
	v_pk_mul_f32 v[2:3], v[18:19], v[66:67]
	v_pk_mul_f32 v[4:5], v[20:21], v[68:69]
	s_waitcnt lgkmcnt(0)
	v_rcp_f32_e32 v18, v70
	v_rcp_f32_e32 v19, v71
	v_rcp_f32_e32 v20, v72
	v_rcp_f32_e32 v21, v73
	global_store_dwordx4 v[0:1], v[2:5], off offset:64
	s_nop 1
	v_pk_mul_f32 v[2:3], v[34:35], v[66:67]
	v_pk_mul_f32 v[4:5], v[36:37], v[68:69]
	global_store_dwordx4 v[0:1], v[2:5], off offset:128
	s_nop 1
	v_pk_mul_f32 v[2:3], v[50:51], v[66:67]
	v_pk_mul_f32 v[4:5], v[52:53], v[68:69]
	global_store_dwordx4 v[0:1], v[2:5], off offset:192
	s_nop 1
	v_pk_mul_f32 v[2:3], v[6:7], v[18:19]
	v_pk_mul_f32 v[4:5], v[8:9], v[20:21]
	global_store_dwordx4 v[0:1], v[2:5], off offset:16
	s_nop 1
	v_pk_mul_f32 v[2:3], v[22:23], v[18:19]
	v_pk_mul_f32 v[4:5], v[24:25], v[20:21]
	global_store_dwordx4 v[0:1], v[2:5], off offset:80
	s_nop 1
	v_pk_mul_f32 v[2:3], v[38:39], v[18:19]
	v_pk_mul_f32 v[4:5], v[40:41], v[20:21]
	global_store_dwordx4 v[0:1], v[2:5], off offset:144
	s_nop 1
	v_pk_mul_f32 v[2:3], v[54:55], v[18:19]
	v_pk_mul_f32 v[4:5], v[56:57], v[20:21]
	global_store_dwordx4 v[0:1], v[2:5], off offset:208
	ds_read_b128 v[2:5], v74 offset:64
	s_waitcnt lgkmcnt(0)
	v_rcp_f32_e32 v6, v2
	v_rcp_f32_e32 v7, v3
	v_rcp_f32_e32 v8, v4
	v_rcp_f32_e32 v9, v5
	v_pk_mul_f32 v[2:3], v[10:11], v[6:7]
	v_mov_b32_e32 v11, v144
	v_pk_mul_f32 v[4:5], v[12:13], v[8:9]
	global_store_dwordx4 v[0:1], v[2:5], off offset:32
	s_nop 1
	v_pk_mul_f32 v[2:3], v[26:27], v[6:7]
	v_pk_mul_f32 v[4:5], v[28:29], v[8:9]
	global_store_dwordx4 v[0:1], v[2:5], off offset:96
	s_nop 1
	v_pk_mul_f32 v[2:3], v[42:43], v[6:7]
	v_pk_mul_f32 v[4:5], v[44:45], v[8:9]
	global_store_dwordx4 v[0:1], v[2:5], off offset:160
	s_nop 1
	v_pk_mul_f32 v[2:3], v[58:59], v[6:7]
	v_pk_mul_f32 v[4:5], v[60:61], v[8:9]
	global_store_dwordx4 v[0:1], v[2:5], off offset:224
	ds_read_b128 v[2:5], v74 offset:96
	s_waitcnt lgkmcnt(0)
	v_rcp_f32_e32 v6, v2
	v_rcp_f32_e32 v7, v3
	v_rcp_f32_e32 v8, v4
	v_rcp_f32_e32 v9, v5
	v_pk_mul_f32 v[2:3], v[14:15], v[6:7]
	v_pk_mul_f32 v[4:5], v[16:17], v[8:9]
	global_store_dwordx4 v[0:1], v[2:5], off offset:48
	s_nop 1
	v_pk_mul_f32 v[2:3], v[30:31], v[6:7]
	v_pk_mul_f32 v[4:5], v[32:33], v[8:9]
	global_store_dwordx4 v[0:1], v[2:5], off offset:112
	s_nop 1
	v_pk_mul_f32 v[2:3], v[46:47], v[6:7]
	v_pk_mul_f32 v[4:5], v[48:49], v[8:9]
	global_store_dwordx4 v[0:1], v[2:5], off offset:176
	s_nop 1
	v_pk_mul_f32 v[2:3], v[62:63], v[6:7]
	v_pk_mul_f32 v[4:5], v[64:65], v[8:9]
	global_store_dwordx4 v[0:1], v[2:5], off offset:240
	v_mov_b32_e32 v0, s0
	ds_read_b32 v0, v0
	v_readlane_b32 s0, v254, 40
	v_bfe_u32 v217, v146, 5, 1
	v_lshlrev_b32_e32 v200, 4, v217
	v_lshlrev_b32_e32 v12, 3, v146
	s_waitcnt lgkmcnt(0)
	v_readfirstlane_b32 s62, v0
	v_mov_b32_e32 v0, s0
	ds_read_b32 v0, v0
	s_movk_i32 s0, 0xffe0
	v_bfe_u32 v5, v12, 5, 2
	v_lshlrev_b32_e32 v6, 4, v146
	v_and_b32_e32 v7, 48, v6
	s_waitcnt lgkmcnt(0)
	v_readfirstlane_b32 s63, v0
	v_ashrrev_i32_e32 v0, 1, v146
	v_and_b32_e32 v215, 0xffffffe0, v0
	v_add_u32_e32 v1, s39, v215
	v_bfi_b32 v0, s0, v0, v146
	v_readfirstlane_b32 s64, v1
	v_ashrrev_i32_e32 v1, 31, v0
	v_lshlrev_b64 v[0:1], 13, v[0:1]
	v_lshl_add_u64 v[0:1], s[52:53], 0, v[0:1]
	v_lshl_add_u64 v[0:1], v[0:1], 0, v[200:201]
	v_and_b32_e32 v10, 0x70, v6
	s_barrier
; __device__ __forceinline__ float bf2f(unsigned short b) { return __uint_as_float(((unsigned)b) << 16); }
; __device__ __forceinline__ int v_st(int k, int c) { const int kk = (k & ~0xC) | ((k & 4) << 1) | ((k & 8) >> 1); return ((kk >> 3) * 4 + (c >> 5)) * 512 + ((kk & 7) * 32 + (c & 31)) * 2; }
; __device__ __forceinline__ int v_rd_base(int lane) { return ((lane & 3) << 3) | (((lane >> 2) & 3) << 6) | (((lane >> 4) & 1) << 5) | (((lane >> 5) & 1) << 8); }
; #define SLOAD(i, k0) do { sr_[i].vs0 = *(const GAS bf16x8*)(&Vh[(long)((k0) + sr) * LDK + sc]); sr_[i].vs1 = *(const GAS bf16x8*)(&Vh[(long)((k0) + 32 + sr) * LDK + sc]); \
;     sr_[i].ks0 = *(const GAS bf16x8*)(&Kh[(long)((k0) + kr) * LDK + kc]); } while (0)
; #define SWRITE(b, i) do { *(bf16x8*)(V_lds + (b) * SHM_V + vst0) = sr_[i].vs0; *(bf16x8*)(V_lds + (b) * SHM_V + vst1) = sr_[i].vs1; \
;     *(bf16x8*)(K_lds + (b) * SHM_K + kst) = sr_[i].ks0; } while (0)
; template <bool GRPB> __device__ __forceinline__ void attn_pass(const float mbK, const float bmax2, const int pass, float* __restrict__ scr, bf16* __restrict__ mixrow, const float lam, const float* __restrict__ gsub, const float one_m_li, ...
;     ...
;   { float qs = 0.f;
; #pragma unroll
;     for (int d0 = 0; d0 < 4; ++d0)
; #pragma unroll
;       for (int j = 0; j < 8; ++j) { const float v = bf2f((unsigned short)qr[d0][j]); qs = fmaf(v, v, qs); }
;     { auto rr = __builtin_amdgcn_permlane32_swap(__float_as_uint(qs), __float_as_uint(qs), false, false); qs = __uint_as_float(rr[0]) + __uint_as_float(rr[1]); }
;     m_reg = __builtin_sqrtf(qs) * mbK + bmax2 + 0.25f; }
;   const int sr = tid >> 4, sc = (tid & 15) * 8, vst0 = v_st(sr, sc), vst1 = v_st(32 + sr, sc);
;   const int kr = tid >> 3, kc = (tid & 7) * 8, kst = KSWZ64(kr, kc * 2);
;   const int vb0 = (int)(uintptr_t)V_lds + v_rd_base(lane);
;   struct { bf16x8 vs0, vs1, ks0; } sr_[2];
;     ...
;   f32x16 pA0, pA1, pB0, pB1; float mnA, mnB, alA, alB; bf16x8 pa0, pa1, pa2, pa3; constexpr int NT = SEQ / KVBLK;
;   __syncthreads();
;   SLOAD(0, 0); SLOAD(1, KVBLK); asm volatile("s_waitcnt vmcnt(0)" ::: "memory"); SWRITE(0, 0); SWRITE(1, 1);
;   SLOAD(0, 2 * KVBLK); asm volatile("s_waitcnt vmcnt(0)" ::: "memory"); SWRITE(2, 0); __syncthreads();
	v_and_b32_e32 v218, 31, v146
	v_add_u32_e32 v147, s64, v218
	s_waitcnt vmcnt(19)
	v_lshlrev_b32_e32 v0, 16, v164
	v_fma_f32 v0, v0, v0, 0
	v_and_b32_e32 v1, 0xffff0000, v164
	v_fmac_f32_e32 v0, v1, v1
	v_lshlrev_b32_e32 v1, 16, v165
	v_fmac_f32_e32 v0, v1, v1
	v_and_b32_e32 v1, 0xffff0000, v165
	v_fmac_f32_e32 v0, v1, v1
	v_lshlrev_b32_e32 v1, 16, v166
	v_fmac_f32_e32 v0, v1, v1
	v_and_b32_e32 v1, 0xffff0000, v166
	v_fmac_f32_e32 v0, v1, v1
	v_lshlrev_b32_e32 v1, 16, v167
	v_fmac_f32_e32 v0, v1, v1
	v_and_b32_e32 v1, 0xffff0000, v167
	v_fmac_f32_e32 v0, v1, v1
	s_waitcnt vmcnt(18)
	v_lshlrev_b32_e32 v1, 16, v160
	v_fmac_f32_e32 v0, v1, v1
	v_and_b32_e32 v1, 0xffff0000, v160
	v_fmac_f32_e32 v0, v1, v1
	v_lshlrev_b32_e32 v1, 16, v161
	v_fmac_f32_e32 v0, v1, v1
	v_and_b32_e32 v1, 0xffff0000, v161
	v_fmac_f32_e32 v0, v1, v1
	v_lshlrev_b32_e32 v1, 16, v162
	v_fmac_f32_e32 v0, v1, v1
	v_and_b32_e32 v1, 0xffff0000, v162
	v_fmac_f32_e32 v0, v1, v1
	v_lshlrev_b32_e32 v1, 16, v163
	v_fmac_f32_e32 v0, v1, v1
	v_and_b32_e32 v1, 0xffff0000, v163
	v_fmac_f32_e32 v0, v1, v1
	s_waitcnt vmcnt(17)
	v_lshlrev_b32_e32 v1, 16, v152
	v_fmac_f32_e32 v0, v1, v1
	v_and_b32_e32 v1, 0xffff0000, v152
	v_fmac_f32_e32 v0, v1, v1
	v_lshlrev_b32_e32 v1, 16, v153
	v_fmac_f32_e32 v0, v1, v1
	v_and_b32_e32 v1, 0xffff0000, v153
	v_fmac_f32_e32 v0, v1, v1
	v_lshlrev_b32_e32 v1, 16, v154
	v_fmac_f32_e32 v0, v1, v1
	v_and_b32_e32 v1, 0xffff0000, v154
	v_fmac_f32_e32 v0, v1, v1
	v_lshlrev_b32_e32 v1, 16, v155
	v_fmac_f32_e32 v0, v1, v1
	v_and_b32_e32 v1, 0xffff0000, v155
	v_fmac_f32_e32 v0, v1, v1
	s_waitcnt vmcnt(16)
	v_lshlrev_b32_e32 v1, 16, v156
	v_fmac_f32_e32 v0, v1, v1
	v_and_b32_e32 v1, 0xffff0000, v156
	v_fmac_f32_e32 v0, v1, v1
	v_lshlrev_b32_e32 v1, 16, v157
	v_fmac_f32_e32 v0, v1, v1
	v_and_b32_e32 v1, 0xffff0000, v157
	v_fmac_f32_e32 v0, v1, v1
	v_lshlrev_b32_e32 v1, 16, v158
	v_fmac_f32_e32 v0, v1, v1
	v_and_b32_e32 v1, 0xffff0000, v158
	v_fmac_f32_e32 v0, v1, v1
	v_lshlrev_b32_e32 v1, 16, v159
	v_fmac_f32_e32 v0, v1, v1
	v_and_b32_e32 v1, 0xffff0000, v159
	v_fmac_f32_e32 v0, v1, v1
	v_mov_b32_e32 v1, v0
	s_nop 1
	v_permlane32_swap_b32_e32 v0, v1
	v_add_f32_e32 v0, v0, v1
	v_cmp_gt_f32_e32 vcc, s10, v0
	v_mul_f32_e32 v1, 0x4f800000, v0
	s_nop 0
	v_cndmask_b32_e32 v0, v0, v1, vcc
	v_sqrt_f32_e32 v1, v0
	s_nop 0
	v_add_u32_e32 v2, -1, v1
	v_fma_f32 v3, -v2, v1, v0
	v_cmp_ge_f32_e64 s[0:1], 0, v3
	v_add_u32_e32 v3, 1, v1
	s_nop 0
	v_cndmask_b32_e64 v2, v1, v2, s[0:1]
	v_fma_f32 v1, -v3, v1, v0
	v_cmp_lt_f32_e64 s[0:1], 0, v1
	s_nop 1
	v_cndmask_b32_e64 v1, v2, v3, s[0:1]
	v_mul_f32_e32 v2, 0x37800000, v1
	v_cndmask_b32_e32 v1, v1, v2, vcc
	v_cmp_class_f32_e32 vcc, v0, v198
	v_and_b32_e32 v2, 0x78, v12
	v_lshlrev_b32_e32 v6, 1, v2
	v_cndmask_b32_e32 v0, v1, v0, vcc
	v_fma_f32 v0, v214, v0, s45
	v_add_f32_e32 v64, 0x3e800000, v0
	v_ashrrev_i32_e32 v0, 4, v146
	v_and_b32_e32 v1, 0xfffff0, v0
	v_lshlrev_b32_e32 v3, 1, v0
	v_and_or_b32 v1, v3, 8, v1
	v_lshrrev_b32_e32 v3, 1, v0
	v_lshrrev_b32_e32 v1, 1, v1
	v_and_b32_e32 v4, 3, v0
	v_or_b32_e32 v1, v1, v5
	v_and_or_b32 v3, v3, 4, v4
	v_lshlrev_b32_e32 v1, 9, v1
	v_lshlrev_b32_e32 v3, 6, v3
	v_add_u32_e32 v4, 32, v0
	v_or3_b32 v221, v1, v3, v7
	v_and_b32_e32 v1, 0xfffff0, v4
	v_lshlrev_b32_e32 v8, 1, v4
	v_and_or_b32 v1, v8, 8, v1
	v_lshrrev_b32_e32 v1, 1, v1
	v_or_b32_e32 v1, v1, v5
	v_lshlrev_b32_e32 v1, 9, v1
	v_ashrrev_i32_e32 v8, 3, v146
	v_or3_b32 v222, v1, v3, v7
	v_lshlrev_b32_e32 v1, 7, v8
	v_and_b32_e32 v3, 0x70, v146
	v_bitop3_b32 v223, v10, v1, v3 bitop3:0xde
	v_ashrrev_i32_e32 v1, 31, v0
	v_lshlrev_b64 v[48:49], 13, v[0:1]
	v_lshl_add_u64 v[0:1], s[50:51], 0, v[48:49]
	v_mov_b32_e32 v7, v144
	v_ashrrev_i32_e32 v5, 31, v4
	v_lshl_add_u64 v[26:27], v[0:1], 0, v[6:7]
	v_lshlrev_b64 v[4:5], 13, v[4:5]
	global_load_dwordx4 v[0:3], v[26:27], off offset:2048
	v_lshl_add_u64 v[4:5], s[50:51], 0, v[4:5]
	v_ashrrev_i32_e32 v9, 31, v8
	s_mov_b32 s0, 0x80000
	v_lshl_add_u64 v[4:5], v[4:5], 0, v[6:7]
	v_lshlrev_b64 v[50:51], 13, v[8:9]
	v_add_co_u32_e32 v14, vcc, s0, v26
	global_load_dwordx4 v[4:7], v[4:5], off offset:2048
	v_lshl_add_u64 v[8:9], s[50:51], 0, v[50:51]
	v_addc_co_u32_e32 v15, vcc, 0, v27, vcc
	s_mov_b32 s1, 0xc0000
	v_lshl_add_u64 v[28:29], v[8:9], 0, v[10:11]
	v_add_co_u32_e32 v18, vcc, s1, v26
	global_load_dwordx4 v[8:11], v[28:29], off offset:1152
	s_nop 0
	v_addc_co_u32_e32 v19, vcc, 0, v27, vcc
	global_load_dwordx4 v[14:17], v[14:15], off offset:2048
	v_add_co_u32_e32 v22, vcc, s0, v28
	global_load_dwordx4 v[18:21], v[18:19], off offset:2048
	s_nop 0
	v_addc_co_u32_e32 v23, vcc, 0, v29, vcc
	global_load_dwordx4 v[22:25], v[22:23], off offset:1152
	v_add_u32_e32 v13, 0, v221
	s_mov_b32 s0, 0x100000
	s_waitcnt vmcnt(3)
	v_add_u32_e32 v30, 0, v222
	s_mov_b32 s1, 0x140000
	v_add_u32_e32 v224, 0, v223
	s_waitcnt vmcnt(5)
	ds_write_b128 v13, v[0:3]
	v_add_co_u32_e32 v0, vcc, s0, v26
	s_waitcnt vmcnt(4)
	ds_write_b128 v30, v[4:7]
	v_addc_co_u32_e32 v1, vcc, 0, v27, vcc
	v_add_co_u32_e32 v4, vcc, s1, v26
	s_waitcnt vmcnt(3)
	ds_write_b128 v224, v[8:11] offset:49152
	v_addc_co_u32_e32 v5, vcc, 0, v27, vcc
	v_add_co_u32_e32 v8, vcc, s0, v28
	global_load_dwordx4 v[0:3], v[0:1], off offset:2048
	s_nop 0
	v_addc_co_u32_e32 v9, vcc, 0, v29, vcc
	global_load_dwordx4 v[4:7], v[4:5], off offset:2048
	s_nop 0
	global_load_dwordx4 v[8:11], v[8:9], off offset:1152
	s_waitcnt vmcnt(5)
	ds_write_b128 v13, v[14:17] offset:16384
	s_waitcnt vmcnt(4)
	ds_write_b128 v30, v[18:21] offset:16384
	s_waitcnt vmcnt(3)
	ds_write_b128 v224, v[22:25] offset:57344
	s_waitcnt vmcnt(0)
	s_waitcnt vmcnt(2)
	ds_write_b128 v13, v[0:3] offset:32768
	s_waitcnt vmcnt(1)
	ds_write_b128 v30, v[4:7] offset:32768
	v_add_u32_e32 v0, 0x10000, v224
	s_waitcnt vmcnt(0)
	ds_write_b128 v0, v[8:11]
	v_lshlrev_b32_e32 v8, 7, v218
	v_and_b32_e32 v9, 0x70, v12
	v_or_b32_e32 v10, 32, v200
	v_bitop3_b32 v229, v10, v8, v9 bitop3:0xde
	v_or_b32_e32 v10, 64, v200
	v_bitop3_b32 v231, v10, v8, v9 bitop3:0xde
	v_or_b32_e32 v10, 0x60, v200
	v_bitop3_b32 v226, v200, v8, v9 bitop3:0xde
	v_bitop3_b32 v240, v10, v8, v9 bitop3:0xde
	v_add_u32_e32 v225, 0, v226
	v_add_u32_e32 v227, 0, v229
	v_add_u32_e32 v228, 0, v231
	v_add_u32_e32 v230, 0, v240
	s_waitcnt lgkmcnt(0)
	s_barrier
; #define SBAR() __builtin_amdgcn_sched_barrier(0)
; __device__ __forceinline__ void partialSM(f32x16& p0, f32x16& p1, float& m_reg, float& mn, float& alpha, int kt0, int qpos, int qw, int hi, const float* tb2, float cL, float cR) {
;   mn = m_reg; alpha = 1.f;
;   const int rel_hi = kt0 + 63 - qw, rel_lo = kt0 - (qw + 31);
;   if (rel_hi <= -91 || rel_lo >= 91) {
;     const float cm = ((rel_hi <= -91) ? cL : cR) - m_reg;
; #pragma unroll
;     for (int r = 0; r < 16; ++r) { p0[r] = fmaf(p0[r], C1, cm); p1[r] = fmaf(p1[r], C1, cm); }
;   } else {
;     const float* tp = tb2 + (kt0 - qpos + 192 + 4 * hi);
; #pragma unroll
;     for (int r4 = 0; r4 < 4; ++r4) {
;       float ta[4], tb[4];
; #pragma unroll
;       for (int i = 0; i < 4; ++i) { ta[i] = tp[8 * r4 + i] - m_reg; tb[i] = tp[32 + 8 * r4 + i] - m_reg; }
; #pragma unroll
;       for (int i = 0; i < 4; ++i) { p0[4 * r4 + i] = fmaf(p0[4 * r4 + i], C1, ta[i]); p1[4 * r4 + i] = fmaf(p1[4 * r4 + i], C1, tb[i]); }
; __device__ __forceinline__ void qkt(f32x16& p0, f32x16& p1, const char* Ks, const bf16x8* qr, int r32, int hi) {
;   bf16x8 ka[4], kb[4];
; #pragma unroll
;   for (int d0 = 0; d0 < 4; ++d0) { const int cb = (d0 * 16 + hi * 8) * 2;
;     ka[d0] = *reinterpret_cast<const bf16x8*>(Ks + KSWZ64(r32, cb)); kb[d0] = *reinterpret_cast<const bf16x8*>(Ks + KSWZ64(32 + r32, cb)); }
;   asm volatile("s_waitcnt lgkmcnt(0)" ::: "memory"); SBAR();
;   p0 = f32x16{}; p1 = f32x16{};
; #pragma unroll
;   for (int d0 = 0; d0 < 4; ++d0) {
;     p0 = __builtin_amdgcn_mfma_f32_32x32x16_bf16(ka[d0], qr[d0], p0, 0, 0, 0);
;     p1 = __builtin_amdgcn_mfma_f32_32x32x16_bf16(kb[d0], qr[d0], p1, 0, 0, 0); }
	ds_read_b128 v[0:3], v225 offset:49152
	ds_read_b128 v[4:7], v225 offset:53248
	ds_read_b128 v[32:35], v227 offset:49152
	ds_read_b128 v[36:39], v227 offset:53248
	ds_read_b128 v[40:43], v228 offset:49152
	ds_read_b128 v[44:47], v228 offset:53248
	ds_read_b128 v[52:55], v230 offset:49152
	ds_read_b128 v[56:59], v230 offset:53248
	s_waitcnt lgkmcnt(0)
	s_waitcnt lgkmcnt(7)
	v_mfma_f32_32x32x16_bf16 v[16:31], v[0:3], v[164:167], 0
	s_add_i32 s4, s64, 0xffffff66
	s_mov_b64 s[0:1], -1
	s_cmp_gt_u32 s4, 0xfffffeec
	s_waitcnt lgkmcnt(6)
	v_mfma_f32_32x32x16_bf16 v[0:15], v[4:7], v[164:167], 0
	s_waitcnt lgkmcnt(5)
	v_mfma_f32_32x32x16_bf16 v[16:31], v[32:35], v[160:163], v[16:31]
	s_waitcnt lgkmcnt(4)
	v_mfma_f32_32x32x16_bf16 v[0:15], v[36:39], v[160:163], v[0:15]
	s_waitcnt lgkmcnt(3)
	v_mfma_f32_32x32x16_bf16 v[16:31], v[40:43], v[152:155], v[16:31]
	s_waitcnt lgkmcnt(2)
	v_mfma_f32_32x32x16_bf16 v[0:15], v[44:47], v[152:155], v[0:15]
	s_waitcnt lgkmcnt(1)
	v_mfma_f32_32x32x16_bf16 v[16:31], v[52:55], v[156:159], v[16:31]
	v_lshlrev_b32_e32 v52, 2, v147
	s_waitcnt lgkmcnt(0)
	v_mfma_f32_32x32x16_bf16 v[0:15], v[56:59], v[156:159], v[0:15]
	s_cbranch_scc0 .LBB0_323
	v_sub_u32_e32 v32, 0, v52
	s_mov_b32 s0, 0x12b00
	v_add3_u32 v53, v32, v200, s0
	ds_read2_b32 v[32:33], v53 offset1:1
	ds_read2_b32 v[54:55], v53 offset0:32 offset1:33
	ds_read2_b32 v[56:57], v53 offset0:34 offset1:35
	ds_read2_b32 v[34:35], v53 offset0:2 offset1:3
	ds_read2_b32 v[36:37], v53 offset0:8 offset1:9
	ds_read2_b32 v[58:59], v53 offset0:40 offset1:41
	ds_read2_b32 v[60:61], v53 offset0:42 offset1:43
	ds_read2_b32 v[38:39], v53 offset0:10 offset1:11
	ds_read2_b32 v[40:41], v53 offset0:16 offset1:17
	ds_read2_b32 v[62:63], v53 offset0:48 offset1:49
	ds_read2_b32 v[66:67], v53 offset0:50 offset1:51
	ds_read2_b32 v[42:43], v53 offset0:18 offset1:19
	ds_read2_b32 v[44:45], v53 offset0:24 offset1:25
	ds_read2_b32 v[46:47], v53 offset0:26 offset1:27
	ds_read2_b32 v[68:69], v53 offset0:58 offset1:59
	ds_read2_b32 v[70:71], v53 offset0:56 offset1:57
	s_waitcnt lgkmcnt(3)
	v_sub_f32_e32 v45, v45, v64
	v_sub_f32_e32 v44, v44, v64
	s_waitcnt lgkmcnt(2)
	v_sub_f32_e32 v47, v47, v64
	v_sub_f32_e32 v46, v46, v64
	v_sub_f32_e32 v41, v41, v64
	v_sub_f32_e32 v40, v40, v64
	v_sub_f32_e32 v43, v43, v64
	v_sub_f32_e32 v42, v42, v64
	v_sub_f32_e32 v37, v37, v64
	v_sub_f32_e32 v36, v36, v64
	v_sub_f32_e32 v39, v39, v64
	v_sub_f32_e32 v38, v38, v64
	v_sub_f32_e32 v33, v33, v64
	v_sub_f32_e32 v32, v32, v64
	v_sub_f32_e32 v35, v35, v64
	v_sub_f32_e32 v34, v34, v64
	s_waitcnt lgkmcnt(0)
	v_sub_f32_e32 v71, v71, v64
	v_sub_f32_e32 v70, v70, v64
	v_sub_f32_e32 v69, v69, v64
	v_sub_f32_e32 v68, v68, v64
	v_sub_f32_e32 v63, v63, v64
	v_sub_f32_e32 v62, v62, v64
	v_sub_f32_e32 v67, v67, v64
	v_sub_f32_e32 v66, v66, v64
	v_sub_f32_e32 v59, v59, v64
	v_sub_f32_e32 v58, v58, v64
	v_sub_f32_e32 v61, v61, v64
	v_sub_f32_e32 v60, v60, v64
	v_sub_f32_e32 v55, v55, v64
	v_sub_f32_e32 v54, v54, v64
	v_sub_f32_e32 v57, v57, v64
	v_sub_f32_e32 v56, v56, v64
	v_pk_fma_f32 v[34:35], v[18:19], s[6:7], v[34:35] op_sel_hi:[1,0,1]
	v_pk_fma_f32 v[32:33], v[16:17], s[6:7], v[32:33] op_sel_hi:[1,0,1]
	v_pk_fma_f32 v[38:39], v[22:23], s[6:7], v[38:39] op_sel_hi:[1,0,1]
	v_pk_fma_f32 v[36:37], v[20:21], s[6:7], v[36:37] op_sel_hi:[1,0,1]
	v_pk_fma_f32 v[42:43], v[26:27], s[6:7], v[42:43] op_sel_hi:[1,0,1]
	v_pk_fma_f32 v[40:41], v[24:25], s[6:7], v[40:41] op_sel_hi:[1,0,1]
	v_pk_fma_f32 v[46:47], v[30:31], s[6:7], v[46:47] op_sel_hi:[1,0,1]
	v_pk_fma_f32 v[44:45], v[28:29], s[6:7], v[44:45] op_sel_hi:[1,0,1]
	v_pk_fma_f32 v[82:83], v[2:3], s[6:7], v[56:57] op_sel_hi:[1,0,1]
	v_pk_fma_f32 v[80:81], v[0:1], s[6:7], v[54:55] op_sel_hi:[1,0,1]
	v_pk_fma_f32 v[86:87], v[6:7], s[6:7], v[60:61] op_sel_hi:[1,0,1]
	v_pk_fma_f32 v[84:85], v[4:5], s[6:7], v[58:59] op_sel_hi:[1,0,1]
	v_pk_fma_f32 v[90:91], v[10:11], s[6:7], v[66:67] op_sel_hi:[1,0,1]
	v_pk_fma_f32 v[88:89], v[8:9], s[6:7], v[62:63] op_sel_hi:[1,0,1]
	v_pk_fma_f32 v[94:95], v[14:15], s[6:7], v[68:69] op_sel_hi:[1,0,1]
	v_pk_fma_f32 v[92:93], v[12:13], s[6:7], v[70:71] op_sel_hi:[1,0,1]
	s_mov_b64 s[0:1], 0

; #define GAS __attribute__((address_space(1)))
; template <bool GRPB> __device__ __forceinline__ void attn_pass(const float mbK, const float bmax2, const int pass, float* __restrict__ scr, bf16* __restrict__ mixrow, const float lam, const float* __restrict__ gsub, const float one_m_li, ...
;     ...
;   const bf16* Qw = Qb + (long)(wid * 32 + r32) * LDK + hi * 8;
; #pragma unroll
;   for (int d0 = 0; d0 < 4; ++d0) qr[d0] = *(const GAS bf16x8*)(Qw + d0 * 16);
;     ...
;   if (pass == 0) {
; #pragma unroll
;     for (int r4 = 0; r4 < 4; ++r4) { const f32x4 lv = *(const f32x4*)(li_e + 8 * r4 + 4 * hi);
;       const f32x4 rl = (f32x4){__builtin_amdgcn_rcpf(lv[0]), __builtin_amdgcn_rcpf(lv[1]), __builtin_amdgcn_rcpf(lv[2]), __builtin_amdgcn_rcpf(lv[3])};
; #pragma unroll
;       for (int d0 = 0; d0 < 4; ++d0) scr4[d0 * 4 + r4] = (f32x4){o[d0][4 * r4 + 0] * rl[0], o[d0][4 * r4 + 1] * rl[1], o[d0][4 * r4 + 2] * rl[2], o[d0][4 * r4 + 3] * rl[3]}; }
.LBB0_373:
	s_or_b64 exec, exec, s[0:1]
	s_movk_i32 s74, 0xffe0
	v_ashrrev_i32_e32 v96, 1, v232
	v_bfi_b32 v96, s74, v96, v232
	v_ashrrev_i32_e32 v97, 31, v96
	v_lshlrev_b64 v[96:97], 13, v[96:97]
	v_lshl_add_u64 v[96:97], s[52:53], 0, v[96:97]
	v_bfe_u32 v98, v232, 5, 1
	v_lshlrev_b32_e32 v98, 4, v98
	v_mov_b32_e32 v99, 0
	v_lshl_add_u64 v[96:97], v[96:97], 0, v[98:99]
	global_load_dwordx4 v[164:167], v[96:97], off offset:128
	global_load_dwordx4 v[160:163], v[96:97], off offset:160
	global_load_dwordx4 v[156:159], v[96:97], off offset:192
	global_load_dwordx4 v[152:155], v[96:97], off offset:224
	s_waitcnt lgkmcnt(0)
	v_add_u32_e32 v76, v66, v180
	ds_read_b128 v[66:69], v76
	ds_read_b128 v[70:73], v76 offset:32
	v_ashrrev_i32_e32 v147, 31, v146
	v_lshlrev_b64 v[0:1], 8, v[146:147]
	v_lshl_add_u64 v[74:75], s[40:41], 0, v[0:1]
	s_waitcnt lgkmcnt(1)
	v_rcp_f32_e32 v66, v66
	v_rcp_f32_e32 v67, v67
	v_rcp_f32_e32 v68, v68
	v_rcp_f32_e32 v69, v69
	v_mov_b32_e32 v146, v232
	v_pk_mul_f32 v[0:1], v[2:3], v[66:67]
	s_movk_i32 s0, 0xffe0
	v_pk_mul_f32 v[2:3], v[4:5], v[68:69]
	global_store_dwordx4 v[74:75], v[0:3], off
	v_mov_b32_e32 v181, v144
	s_mov_b32 s1, 0xc0000
	v_pk_mul_f32 v[0:1], v[18:19], v[66:67]
	s_waitcnt lgkmcnt(0)
	v_rcp_f32_e32 v18, v70
	v_rcp_f32_e32 v19, v71
	v_pk_mul_f32 v[2:3], v[20:21], v[68:69]
	global_store_dwordx4 v[74:75], v[0:3], off offset:64
	s_nop 1
	v_pk_mul_f32 v[0:1], v[34:35], v[66:67]
	v_pk_mul_f32 v[2:3], v[36:37], v[68:69]
	v_rcp_f32_e32 v34, v72
	v_rcp_f32_e32 v35, v73
	global_store_dwordx4 v[74:75], v[0:3], off offset:128
	s_nop 1
	v_pk_mul_f32 v[0:1], v[50:51], v[66:67]
	v_pk_mul_f32 v[2:3], v[52:53], v[68:69]
	global_store_dwordx4 v[74:75], v[0:3], off offset:192
	s_nop 1
	v_pk_mul_f32 v[0:1], v[6:7], v[18:19]
	ds_read_b128 v[4:7], v76 offset:64
	v_pk_mul_f32 v[2:3], v[8:9], v[34:35]
	global_store_dwordx4 v[74:75], v[0:3], off offset:16
	s_nop 1
	v_pk_mul_f32 v[0:1], v[22:23], v[18:19]
	v_pk_mul_f32 v[2:3], v[24:25], v[34:35]
	global_store_dwordx4 v[74:75], v[0:3], off offset:80
	s_nop 1
	v_pk_mul_f32 v[0:1], v[38:39], v[18:19]
	v_pk_mul_f32 v[2:3], v[40:41], v[34:35]
	global_store_dwordx4 v[74:75], v[0:3], off offset:144
	s_nop 1
	v_pk_mul_f32 v[0:1], v[54:55], v[18:19]
	ds_read_b128 v[18:21], v76 offset:96
	s_waitcnt lgkmcnt(1)
	v_rcp_f32_e32 v4, v4
	v_rcp_f32_e32 v5, v5
	v_rcp_f32_e32 v6, v6
	v_rcp_f32_e32 v7, v7
	v_pk_mul_f32 v[2:3], v[56:57], v[34:35]
	global_store_dwordx4 v[74:75], v[0:3], off offset:208
	s_waitcnt lgkmcnt(0)
	v_rcp_f32_e32 v8, v20
	v_rcp_f32_e32 v9, v21
	v_pk_mul_f32 v[0:1], v[10:11], v[4:5]
	v_pk_mul_f32 v[2:3], v[12:13], v[6:7]
	global_store_dwordx4 v[74:75], v[0:3], off offset:32
	s_nop 1
	v_pk_mul_f32 v[0:1], v[26:27], v[4:5]
	v_pk_mul_f32 v[2:3], v[28:29], v[6:7]
	global_store_dwordx4 v[74:75], v[0:3], off offset:96
	s_nop 1
	v_pk_mul_f32 v[0:1], v[42:43], v[4:5]
	v_pk_mul_f32 v[2:3], v[44:45], v[6:7]
	global_store_dwordx4 v[74:75], v[0:3], off offset:160
	v_mov_b32_e32 v43, v144
	s_nop 0
	v_pk_mul_f32 v[0:1], v[58:59], v[4:5]
	v_rcp_f32_e32 v4, v18
	v_rcp_f32_e32 v5, v19
	v_pk_mul_f32 v[2:3], v[60:61], v[6:7]
	global_store_dwordx4 v[74:75], v[0:3], off offset:224
	s_nop 1
	v_pk_mul_f32 v[0:1], v[14:15], v[4:5]
	v_pk_mul_f32 v[2:3], v[16:17], v[8:9]
	global_store_dwordx4 v[74:75], v[0:3], off offset:48
	s_nop 1
	v_pk_mul_f32 v[0:1], v[30:31], v[4:5]
	v_pk_mul_f32 v[2:3], v[32:33], v[8:9]
	global_store_dwordx4 v[74:75], v[0:3], off offset:112
	s_nop 1
	v_pk_mul_f32 v[0:1], v[46:47], v[4:5]
	v_pk_mul_f32 v[2:3], v[48:49], v[8:9]
	global_store_dwordx4 v[74:75], v[0:3], off offset:176
	s_nop 1
	v_pk_mul_f32 v[0:1], v[62:63], v[4:5]
	v_pk_mul_f32 v[2:3], v[64:65], v[8:9]
	global_store_dwordx4 v[74:75], v[0:3], off offset:240
	s_nop 0
	v_bfe_u32 v190, v146, 5, 1
	v_ashrrev_i32_e32 v2, 1, v146
	v_bfi_b32 v0, s0, v2, v146
	v_ashrrev_i32_e32 v1, 31, v0
	v_lshlrev_b64 v[0:1], 13, v[0:1]
	v_lshl_add_u64 v[0:1], s[52:53], 0, v[0:1]
	v_lshlrev_b32_e32 v180, 4, v190
	v_lshl_add_u64 v[0:1], v[0:1], 0, v[180:181]
	v_readlane_b32 s0, v254, 39
	v_and_b32_e32 v215, 0xffffffe0, v2
	v_ashrrev_i32_e32 v36, 4, v146
	v_mov_b32_e32 v3, s0
	v_readlane_b32 s0, v254, 40
	v_lshlrev_b32_e32 v45, 3, v146
	v_ashrrev_i32_e32 v37, 31, v36
	v_mov_b32_e32 v4, s0
	ds_read_b32 v3, v3
	ds_read_b32 v4, v4
	v_lshlrev_b64 v[48:49], 13, v[36:37]
	v_ashrrev_i32_e32 v40, 3, v146
	s_waitcnt lgkmcnt(1)
	v_readfirstlane_b32 s52, v3
	v_mov_b32_e32 v3, v144
	s_mov_b32 s0, 0x80000
	v_ashrrev_i32_e32 v41, 31, v40
	v_lshlrev_b32_e32 v46, 4, v146
	v_lshlrev_b64 v[50:51], 13, v[40:41]
	v_add_u32_e32 v38, 32, v36
	v_and_b32_e32 v42, 0x70, v46
	v_lshl_add_u64 v[8:9], s[50:51], 0, v[50:51]
	v_ashrrev_i32_e32 v39, 31, v38
	v_lshl_add_u64 v[32:33], v[8:9], 0, v[42:43]
	s_waitcnt lgkmcnt(0)
	v_readfirstlane_b32 s53, v4
	s_barrier
; __device__ __forceinline__ float bf2f(unsigned short b) { return __uint_as_float(((unsigned)b) << 16); }
; __device__ __forceinline__ int v_st(int k, int c) { const int kk = (k & ~0xC) | ((k & 4) << 1) | ((k & 8) >> 1); return ((kk >> 3) * 4 + (c >> 5)) * 512 + ((kk & 7) * 32 + (c & 31)) * 2; }
; __device__ __forceinline__ int v_rd_base(int lane) { return ((lane & 3) << 3) | (((lane >> 2) & 3) << 6) | (((lane >> 4) & 1) << 5) | (((lane >> 5) & 1) << 8); }
; #define SLOAD(i, k0) do { sr_[i].vs0 = *(const GAS bf16x8*)(&Vh[(long)((k0) + sr) * LDK + sc]); sr_[i].vs1 = *(const GAS bf16x8*)(&Vh[(long)((k0) + 32 + sr) * LDK + sc]); \
;     sr_[i].ks0 = *(const GAS bf16x8*)(&Kh[(long)((k0) + kr) * LDK + kc]); } while (0)
; #define SWRITE(b, i) do { *(bf16x8*)(V_lds + (b) * SHM_V + vst0) = sr_[i].vs0; *(bf16x8*)(V_lds + (b) * SHM_V + vst1) = sr_[i].vs1; \
;     *(bf16x8*)(K_lds + (b) * SHM_K + kst) = sr_[i].ks0; } while (0)
; template <bool GRPB> __device__ __forceinline__ void attn_pass(const float mbK, const float bmax2, const int pass, float* __restrict__ scr, bf16* __restrict__ mixrow, const float lam, const float* __restrict__ gsub, const float one_m_li, ...
;     ...
;   { float qs = 0.f;
; #pragma unroll
;     for (int d0 = 0; d0 < 4; ++d0)
; #pragma unroll
;       for (int j = 0; j < 8; ++j) { const float v = bf2f((unsigned short)qr[d0][j]); qs = fmaf(v, v, qs); }
;     { auto rr = __builtin_amdgcn_permlane32_swap(__float_as_uint(qs), __float_as_uint(qs), false, false); qs = __uint_as_float(rr[0]) + __uint_as_float(rr[1]); }
;     m_reg = __builtin_sqrtf(qs) * mbK + bmax2 + 0.25f; }
;   const int sr = tid >> 4, sc = (tid & 15) * 8, vst0 = v_st(sr, sc), vst1 = v_st(32 + sr, sc);
;   const int kr = tid >> 3, kc = (tid & 7) * 8, kst = KSWZ64(kr, kc * 2);
;   const int vb0 = (int)(uintptr_t)V_lds + v_rd_base(lane);
;   struct { bf16x8 vs0, vs1, ks0; } sr_[2];
;     ...
;   f32x16 pA0, pA1, pB0, pB1; float mnA, mnB, alA, alB; bf16x8 pa0, pa1, pa2, pa3; constexpr int NT = SEQ / KVBLK;
;   __syncthreads();
;   SLOAD(0, 0); SLOAD(1, KVBLK); asm volatile("s_waitcnt vmcnt(0)" ::: "memory"); SWRITE(0, 0); SWRITE(1, 1);
;   SLOAD(0, 2 * KVBLK); asm volatile("s_waitcnt vmcnt(0)" ::: "memory"); SWRITE(2, 0); __syncthreads();
	v_add_u32_e32 v41, s39, v215
	v_and_b32_e32 v181, 31, v146
	v_readfirstlane_b32 s39, v41
	s_waitcnt vmcnt(19)
	v_lshlrev_b32_e32 v0, 16, v164
	v_and_b32_e32 v1, 0xffff0000, v164
	v_fma_f32 v44, v0, v0, 0
	v_lshlrev_b32_e32 v2, 16, v165
	v_fmac_f32_e32 v44, v1, v1
	v_fmac_f32_e32 v44, v2, v2
	v_and_b32_e32 v0, 0xffff0000, v165
	v_fmac_f32_e32 v44, v0, v0
	v_lshlrev_b32_e32 v0, 16, v166
	v_fmac_f32_e32 v44, v0, v0
	v_and_b32_e32 v0, 0xffff0000, v166
	v_fmac_f32_e32 v44, v0, v0
	v_lshlrev_b32_e32 v0, 16, v167
	v_fmac_f32_e32 v44, v0, v0
	v_and_b32_e32 v0, 0xffff0000, v167
	v_fmac_f32_e32 v44, v0, v0
	s_waitcnt vmcnt(18)
	v_lshlrev_b32_e32 v0, 16, v160
	v_fmac_f32_e32 v44, v0, v0
	v_and_b32_e32 v0, 0xffff0000, v160
	v_fmac_f32_e32 v44, v0, v0
	v_lshlrev_b32_e32 v0, 16, v161
	v_fmac_f32_e32 v44, v0, v0
	v_and_b32_e32 v0, 0xffff0000, v161
	v_fmac_f32_e32 v44, v0, v0
	v_lshlrev_b32_e32 v0, 16, v162
	v_fmac_f32_e32 v44, v0, v0
	v_and_b32_e32 v0, 0xffff0000, v162
	v_fmac_f32_e32 v44, v0, v0
	v_lshlrev_b32_e32 v0, 16, v163
	v_fmac_f32_e32 v44, v0, v0
	v_and_b32_e32 v0, 0xffff0000, v163
	v_fmac_f32_e32 v44, v0, v0
	s_waitcnt vmcnt(17)
	v_lshlrev_b32_e32 v0, 16, v156
	v_fmac_f32_e32 v44, v0, v0
	v_and_b32_e32 v0, 0xffff0000, v156
	v_fmac_f32_e32 v44, v0, v0
	v_lshlrev_b32_e32 v0, 16, v157
	v_fmac_f32_e32 v44, v0, v0
	v_and_b32_e32 v0, 0xffff0000, v157
	v_fmac_f32_e32 v44, v0, v0
	v_lshlrev_b32_e32 v0, 16, v158
	v_fmac_f32_e32 v44, v0, v0
	v_and_b32_e32 v0, 0xffff0000, v158
	v_fmac_f32_e32 v44, v0, v0
	v_lshlrev_b32_e32 v0, 16, v159
	v_and_b32_e32 v2, 0x78, v45
	v_fmac_f32_e32 v44, v0, v0
	v_lshl_add_u64 v[0:1], s[50:51], 0, v[48:49]
	v_lshlrev_b32_e32 v2, 1, v2
	v_lshl_add_u64 v[24:25], v[0:1], 0, v[2:3]
	v_add_co_u32_e32 v12, vcc, s0, v24
	v_lshlrev_b64 v[0:1], 13, v[38:39]
	s_nop 0
	v_addc_co_u32_e32 v13, vcc, 0, v25, vcc
	v_add_co_u32_e32 v16, vcc, s1, v24
	v_lshl_add_u64 v[0:1], s[50:51], 0, v[0:1]
	s_nop 0
	v_addc_co_u32_e32 v17, vcc, 0, v25, vcc
	v_add_co_u32_e32 v20, vcc, s0, v32
	s_mov_b32 s0, 0x100000
	s_nop 0
	v_addc_co_u32_e32 v21, vcc, 0, v33, vcc
	v_lshl_add_u64 v[4:5], v[0:1], 0, v[2:3]
	v_add_co_u32_e32 v26, vcc, s0, v24
	global_load_dwordx4 v[0:3], v[24:25], off offset:2048
	s_nop 0
	global_load_dwordx4 v[4:7], v[4:5], off offset:2048
	s_nop 0
	global_load_dwordx4 v[8:11], v[32:33], off offset:1152
	s_nop 0
	global_load_dwordx4 v[12:15], v[12:13], off offset:2048
	s_nop 0
	global_load_dwordx4 v[16:19], v[16:17], off offset:2048
	s_nop 0
	global_load_dwordx4 v[20:23], v[20:21], off offset:1152
	v_addc_co_u32_e32 v27, vcc, 0, v25, vcc
	s_mov_b32 s1, 0x140000
	v_add_co_u32_e32 v28, vcc, s1, v24
	s_waitcnt vmcnt(0)
	v_and_b32_e32 v37, 0xffff0000, v159
	s_nop 0
	v_addc_co_u32_e32 v29, vcc, 0, v25, vcc
	v_add_co_u32_e32 v32, vcc, s0, v32
	global_load_dwordx4 v[24:27], v[26:27], off offset:2048
	s_nop 0
	global_load_dwordx4 v[28:31], v[28:29], off offset:2048
	v_addc_co_u32_e32 v33, vcc, 0, v33, vcc
	global_load_dwordx4 v[32:35], v[32:33], off offset:1152
	v_fmac_f32_e32 v44, v37, v37
	s_waitcnt vmcnt(9)
	v_lshlrev_b32_e32 v37, 16, v152
	v_fmac_f32_e32 v44, v37, v37
	v_and_b32_e32 v37, 0xffff0000, v152
	v_fmac_f32_e32 v44, v37, v37
	v_lshlrev_b32_e32 v37, 16, v153
	v_fmac_f32_e32 v44, v37, v37
	v_and_b32_e32 v37, 0xffff0000, v153
	v_fmac_f32_e32 v44, v37, v37
	v_lshlrev_b32_e32 v37, 16, v154
	v_fmac_f32_e32 v44, v37, v37
	v_and_b32_e32 v37, 0xffff0000, v154
	v_fmac_f32_e32 v44, v37, v37
	v_lshlrev_b32_e32 v37, 16, v155
	v_fmac_f32_e32 v44, v37, v37
	v_and_b32_e32 v37, 0xffff0000, v155
	v_fmac_f32_e32 v44, v37, v37
	v_mov_b32_e32 v37, v44
	s_nop 1
	v_permlane32_swap_b32_e32 v44, v37
	v_add_f32_e32 v37, v44, v37
	v_mul_f32_e32 v39, 0x4f800000, v37
	v_cmp_gt_f32_e32 vcc, s10, v37
	v_add_u32_e32 v192, s39, v181
	s_nop 0
	v_cndmask_b32_e32 v37, v37, v39, vcc
	v_sqrt_f32_e32 v39, v37
	s_nop 0
	v_add_u32_e32 v41, -1, v39
	v_fma_f32 v43, -v41, v39, v37
	v_cmp_ge_f32_e64 s[0:1], 0, v43
	v_add_u32_e32 v43, 1, v39
	s_nop 0
	v_cndmask_b32_e64 v41, v39, v41, s[0:1]
	v_fma_f32 v39, -v43, v39, v37
	v_cmp_lt_f32_e64 s[0:1], 0, v39
	s_nop 1
	v_cndmask_b32_e64 v39, v41, v43, s[0:1]
	v_mul_f32_e32 v41, 0x37800000, v39
	v_cndmask_b32_e32 v39, v39, v41, vcc
	v_cmp_class_f32_e32 vcc, v37, v198
	v_bfe_u32 v41, v45, 5, 2
	s_nop 0
	v_cndmask_b32_e32 v37, v39, v37, vcc
	v_fma_f32 v37, v214, v37, s45
	v_add_f32_e32 v64, 0x3e800000, v37
	v_and_b32_e32 v37, 0xfffff0, v36
	v_lshlrev_b32_e32 v39, 1, v36
	v_and_or_b32 v37, v39, 8, v37
	v_lshrrev_b32_e32 v39, 1, v36
	v_lshrrev_b32_e32 v37, 1, v37
	v_and_b32_e32 v36, 3, v36
	v_or_b32_e32 v37, v37, v41
	v_and_or_b32 v36, v39, 4, v36
	v_lshlrev_b32_e32 v37, 9, v37
	v_lshlrev_b32_e32 v36, 6, v36
	v_and_b32_e32 v39, 48, v46
	v_or3_b32 v193, v37, v36, v39
	v_and_b32_e32 v37, 0xfffff0, v38
	v_lshlrev_b32_e32 v38, 1, v38
	v_and_or_b32 v37, v38, 8, v37
	v_lshrrev_b32_e32 v37, 1, v37
	v_or_b32_e32 v37, v37, v41
	v_lshlrev_b32_e32 v37, 9, v37
	v_or3_b32 v194, v37, v36, v39
	v_lshlrev_b32_e32 v36, 7, v40
	v_and_b32_e32 v37, 0x70, v146
	v_bitop3_b32 v195, v42, v36, v37 bitop3:0xde
	v_add_u32_e32 v36, 0, v193
	s_waitcnt vmcnt(8)
	ds_write_b128 v36, v[0:3]
	v_add_u32_e32 v0, 0, v194
	v_add_u32_e32 v200, 0, v195
	s_waitcnt vmcnt(7)
	ds_write_b128 v0, v[4:7]
	s_waitcnt vmcnt(6)
	ds_write_b128 v200, v[8:11] offset:49152
	s_waitcnt vmcnt(5)
	ds_write_b128 v36, v[12:15] offset:16384
	s_waitcnt vmcnt(4)
	ds_write_b128 v0, v[16:19] offset:16384
	s_waitcnt vmcnt(3)
	ds_write_b128 v200, v[20:23] offset:57344
	v_lshlrev_b32_e32 v8, 7, v181
	v_and_b32_e32 v9, 0x70, v45
	v_or_b32_e32 v10, 32, v180
	v_bitop3_b32 v206, v10, v8, v9 bitop3:0xde
	v_or_b32_e32 v10, 64, v180
	v_bitop3_b32 v208, v10, v8, v9 bitop3:0xde
	v_or_b32_e32 v10, 0x60, v180
	v_bitop3_b32 v203, v180, v8, v9 bitop3:0xde
	v_bitop3_b32 v209, v10, v8, v9 bitop3:0xde
	s_waitcnt vmcnt(0)
	s_waitcnt vmcnt(2)
	ds_write_b128 v36, v[24:27] offset:32768
	s_waitcnt vmcnt(1)
	ds_write_b128 v0, v[28:31] offset:32768
	v_add_u32_e32 v0, 0x10000, v200
	v_add_u32_e32 v202, 0, v203
	v_add_u32_e32 v204, 0, v206
	v_add_u32_e32 v205, 0, v208
	v_add_u32_e32 v207, 0, v209
	s_waitcnt vmcnt(0)
	ds_write_b128 v0, v[32:35]
	s_waitcnt lgkmcnt(0)
	s_barrier
; #define SBAR() __builtin_amdgcn_sched_barrier(0)
; __device__ __forceinline__ void partialSM(f32x16& p0, f32x16& p1, float& m_reg, float& mn, float& alpha, int kt0, int qpos, int qw, int hi, const float* tb2, float cL, float cR) {
;   mn = m_reg; alpha = 1.f;
;   const int rel_hi = kt0 + 63 - qw, rel_lo = kt0 - (qw + 31);
;   if (rel_hi <= -91 || rel_lo >= 91) {
;     const float cm = ((rel_hi <= -91) ? cL : cR) - m_reg;
; #pragma unroll
;     for (int r = 0; r < 16; ++r) { p0[r] = fmaf(p0[r], C1, cm); p1[r] = fmaf(p1[r], C1, cm); }
;   } else {
;     const float* tp = tb2 + (kt0 - qpos + 192 + 4 * hi);
; #pragma unroll
;     for (int r4 = 0; r4 < 4; ++r4) {
;       float ta[4], tb[4];
; #pragma unroll
;       for (int i = 0; i < 4; ++i) { ta[i] = tp[8 * r4 + i] - m_reg; tb[i] = tp[32 + 8 * r4 + i] - m_reg; }
; #pragma unroll
;       for (int i = 0; i < 4; ++i) { p0[4 * r4 + i] = fmaf(p0[4 * r4 + i], C1, ta[i]); p1[4 * r4 + i] = fmaf(p1[4 * r4 + i], C1, tb[i]); }
; __device__ __forceinline__ void qkt(f32x16& p0, f32x16& p1, const char* Ks, const bf16x8* qr, int r32, int hi) {
;   bf16x8 ka[4], kb[4];
; #pragma unroll
;   for (int d0 = 0; d0 < 4; ++d0) { const int cb = (d0 * 16 + hi * 8) * 2;
;     ka[d0] = *reinterpret_cast<const bf16x8*>(Ks + KSWZ64(r32, cb)); kb[d0] = *reinterpret_cast<const bf16x8*>(Ks + KSWZ64(32 + r32, cb)); }
;   asm volatile("s_waitcnt lgkmcnt(0)" ::: "memory"); SBAR();
;   p0 = f32x16{}; p1 = f32x16{};
; #pragma unroll
;   for (int d0 = 0; d0 < 4; ++d0) {
;     p0 = __builtin_amdgcn_mfma_f32_32x32x16_bf16(ka[d0], qr[d0], p0, 0, 0, 0);
;     p1 = __builtin_amdgcn_mfma_f32_32x32x16_bf16(kb[d0], qr[d0], p1, 0, 0, 0); }
	ds_read_b128 v[0:3], v202 offset:49152
	ds_read_b128 v[4:7], v202 offset:53248
	ds_read_b128 v[32:35], v204 offset:49152
	ds_read_b128 v[36:39], v204 offset:53248
	ds_read_b128 v[40:43], v205 offset:49152
	ds_read_b128 v[44:47], v205 offset:53248
	ds_read_b128 v[52:55], v207 offset:49152
	ds_read_b128 v[56:59], v207 offset:53248
	s_waitcnt lgkmcnt(0)
	s_waitcnt lgkmcnt(7)
	v_mfma_f32_32x32x16_bf16 v[16:31], v[0:3], v[164:167], 0
	s_add_i32 s4, s39, 0xffffff66
	s_mov_b64 s[0:1], -1
	s_cmp_gt_u32 s4, 0xfffffeec
	s_waitcnt lgkmcnt(6)
	v_mfma_f32_32x32x16_bf16 v[0:15], v[4:7], v[164:167], 0
	s_waitcnt lgkmcnt(5)
	v_mfma_f32_32x32x16_bf16 v[16:31], v[32:35], v[160:163], v[16:31]
	s_waitcnt lgkmcnt(4)
	v_mfma_f32_32x32x16_bf16 v[0:15], v[36:39], v[160:163], v[0:15]
	s_waitcnt lgkmcnt(3)
	v_mfma_f32_32x32x16_bf16 v[16:31], v[40:43], v[156:159], v[16:31]
	s_waitcnt lgkmcnt(2)
	v_mfma_f32_32x32x16_bf16 v[0:15], v[44:47], v[156:159], v[0:15]
	s_waitcnt lgkmcnt(1)
	v_mfma_f32_32x32x16_bf16 v[16:31], v[52:55], v[152:155], v[16:31]
	v_lshlrev_b32_e32 v52, 2, v192
	s_waitcnt lgkmcnt(0)
	v_mfma_f32_32x32x16_bf16 v[0:15], v[56:59], v[152:155], v[0:15]
	s_cbranch_scc0 .LBB0_375
	v_sub_u32_e32 v32, 0, v52
	s_mov_b32 s0, 0x12b00
	v_add3_u32 v53, v32, v180, s0
	ds_read2_b32 v[32:33], v53 offset1:1
	ds_read2_b32 v[54:55], v53 offset0:32 offset1:33
	ds_read2_b32 v[56:57], v53 offset0:34 offset1:35
	ds_read2_b32 v[34:35], v53 offset0:2 offset1:3
	ds_read2_b32 v[36:37], v53 offset0:8 offset1:9
	ds_read2_b32 v[58:59], v53 offset0:40 offset1:41
	ds_read2_b32 v[60:61], v53 offset0:42 offset1:43
	ds_read2_b32 v[38:39], v53 offset0:10 offset1:11
	ds_read2_b32 v[40:41], v53 offset0:16 offset1:17
	ds_read2_b32 v[62:63], v53 offset0:48 offset1:49
	ds_read2_b32 v[66:67], v53 offset0:50 offset1:51
	ds_read2_b32 v[42:43], v53 offset0:18 offset1:19
	ds_read2_b32 v[44:45], v53 offset0:24 offset1:25
	ds_read2_b32 v[46:47], v53 offset0:26 offset1:27
	ds_read2_b32 v[68:69], v53 offset0:58 offset1:59
	ds_read2_b32 v[70:71], v53 offset0:56 offset1:57
	s_waitcnt lgkmcnt(3)
	v_sub_f32_e32 v45, v45, v64
	v_sub_f32_e32 v44, v44, v64
	s_waitcnt lgkmcnt(2)
	v_sub_f32_e32 v47, v47, v64
	v_sub_f32_e32 v46, v46, v64
	v_sub_f32_e32 v41, v41, v64
	v_sub_f32_e32 v40, v40, v64
	v_sub_f32_e32 v43, v43, v64
	v_sub_f32_e32 v42, v42, v64
	v_sub_f32_e32 v37, v37, v64
	v_sub_f32_e32 v36, v36, v64
	v_sub_f32_e32 v39, v39, v64
	v_sub_f32_e32 v38, v38, v64
	v_sub_f32_e32 v33, v33, v64
	v_sub_f32_e32 v32, v32, v64
	v_sub_f32_e32 v35, v35, v64
	v_sub_f32_e32 v34, v34, v64
	s_waitcnt lgkmcnt(0)
	v_sub_f32_e32 v71, v71, v64
	v_sub_f32_e32 v70, v70, v64
	v_sub_f32_e32 v69, v69, v64
	v_sub_f32_e32 v68, v68, v64
	v_sub_f32_e32 v63, v63, v64
	v_sub_f32_e32 v62, v62, v64
	v_sub_f32_e32 v67, v67, v64
	v_sub_f32_e32 v66, v66, v64
	v_sub_f32_e32 v59, v59, v64
	v_sub_f32_e32 v58, v58, v64
	v_sub_f32_e32 v61, v61, v64
	v_sub_f32_e32 v60, v60, v64
	v_sub_f32_e32 v55, v55, v64
	v_sub_f32_e32 v54, v54, v64
	v_sub_f32_e32 v57, v57, v64
	v_sub_f32_e32 v56, v56, v64
	v_pk_fma_f32 v[34:35], v[18:19], s[6:7], v[34:35] op_sel_hi:[1,0,1]
	v_pk_fma_f32 v[32:33], v[16:17], s[6:7], v[32:33] op_sel_hi:[1,0,1]
	v_pk_fma_f32 v[38:39], v[22:23], s[6:7], v[38:39] op_sel_hi:[1,0,1]
	v_pk_fma_f32 v[36:37], v[20:21], s[6:7], v[36:37] op_sel_hi:[1,0,1]
	v_pk_fma_f32 v[42:43], v[26:27], s[6:7], v[42:43] op_sel_hi:[1,0,1]
	v_pk_fma_f32 v[40:41], v[24:25], s[6:7], v[40:41] op_sel_hi:[1,0,1]
	v_pk_fma_f32 v[46:47], v[30:31], s[6:7], v[46:47] op_sel_hi:[1,0,1]
	v_pk_fma_f32 v[44:45], v[28:29], s[6:7], v[44:45] op_sel_hi:[1,0,1]
	v_pk_fma_f32 v[82:83], v[2:3], s[6:7], v[56:57] op_sel_hi:[1,0,1]
	v_pk_fma_f32 v[80:81], v[0:1], s[6:7], v[54:55] op_sel_hi:[1,0,1]
	v_pk_fma_f32 v[86:87], v[6:7], s[6:7], v[60:61] op_sel_hi:[1,0,1]
	v_pk_fma_f32 v[84:85], v[4:5], s[6:7], v[58:59] op_sel_hi:[1,0,1]
	v_pk_fma_f32 v[90:91], v[10:11], s[6:7], v[66:67] op_sel_hi:[1,0,1]
	v_pk_fma_f32 v[88:89], v[8:9], s[6:7], v[62:63] op_sel_hi:[1,0,1]
	v_pk_fma_f32 v[94:95], v[14:15], s[6:7], v[68:69] op_sel_hi:[1,0,1]
	v_pk_fma_f32 v[92:93], v[12:13], s[6:7], v[70:71] op_sel_hi:[1,0,1]
	s_mov_b64 s[0:1], 0
